# v51 + norm1/norm2 loops: gain in registers, adaLN shift/scale staged in LDS per block (ds_read in row loop), X prefetch waited at row end
# speedup vs baseline: 1.1232x; 1.0172x over previous
.LBB0_130:
	s_andn2_b64 vcc, exec, s[40:41]
	s_cbranch_vccnz .LBB0_137
	s_waitcnt vmcnt(0) lgkmcnt(0)
	v_mov_b32_e32 v11, v168
	v_mov_b32_e32 v0, v168
	v_readlane_b32 s0, v254, 7
	v_ashrrev_i32_e32 v10, 6, v0
	s_nop 0
	v_add_u32_e32 v8, s0, v10
	v_readlane_b32 s0, v254, 46
	v_readlane_b32 s1, v254, 47
	s_movk_i32 s1, 0x3000
	s_nop 0
	v_cmp_gt_i32_e32 vcc, s1, v8
	s_and_saveexec_b64 s[40:41], vcc
	s_cbranch_execz .LBB0_136
	v_ashrrev_i32_e32 v9, 31, v8
	v_readlane_b32 s44, v254, 48
	v_lshlrev_b32_e32 v3, 2, v11
	v_lshlrev_b64 v[0:1], 12, v[8:9]
	v_readlane_b32 s46, v254, 50
	v_readlane_b32 s47, v254, 51
	v_and_b32_e32 v12, 0xfc, v3
	v_lshlrev_b32_e32 v14, 2, v12
	v_lshl_add_u64 v[0:1], s[46:47], 0, v[0:1]
	v_mov_b32_e32 v15, v2
	v_lshl_add_u64 v[0:1], v[0:1], 0, v[14:15]
	global_load_dwordx4 v[32:35], v[0:1], off
	global_load_dwordx4 v[28:31], v[0:1], off offset:1024
	global_load_dwordx4 v[24:27], v[0:1], off offset:2048
	global_load_dwordx4 v[4:7], v[0:1], off offset:3072
	v_lshlrev_b64 v[8:9], 11, v[8:9]
	v_and_b32_e32 v11, 63, v11
	v_readlane_b32 s0, v252, 32
	v_lshl_or_b32 v8, v11, 3, v8
	v_readlane_b32 s1, v252, 33
	v_cmp_lt_i32_e32 vcc, v180, v182
	s_add_u32 s2, s14, s38
	v_lshl_add_u64 v[36:37], s[0:1], 0, v[8:9]
	v_readlane_b32 s0, v254, 8
	v_cndmask_b32_e32 v0, v179, v180, vcc
	v_cmp_lt_i32_e32 vcc, v183, v182
	v_add_u32_e32 v41, s0, v10
	v_readlane_b32 s0, v254, 2
	v_lshlrev_b32_e32 v3, 2, v0
	v_cndmask_b32_e32 v0, v179, v183, vcc
	v_add_u32_e32 v8, s0, v10
	v_cmp_lt_i32_e32 vcc, v184, v182
	v_ashrrev_i32_e32 v9, 31, v8
	v_lshlrev_b32_e32 v49, 2, v0
	v_cndmask_b32_e32 v0, v179, v184, vcc
	v_cmp_lt_i32_e32 vcc, v185, v182
	v_lshlrev_b64 v[8:9], 12, v[8:9]
	v_readlane_b32 s0, v250, 51
	v_lshlrev_b32_e32 v54, 2, v0
	v_cndmask_b32_e32 v0, v179, v185, vcc
	v_cmp_lt_i32_e32 vcc, v186, v182
	v_lshl_or_b32 v8, v11, 4, v8
	v_readlane_b32 s1, v250, 52
	v_lshlrev_b32_e32 v55, 2, v0
	v_cndmask_b32_e32 v0, v179, v186, vcc
	v_cmp_lt_i32_e32 vcc, v187, v182
	v_lshl_add_u64 v[38:39], s[0:1], 0, v[8:9]
	v_readlane_b32 s0, v254, 46
	s_addc_u32 s3, s15, s39
	v_lshlrev_b32_e32 v56, 2, v0
	v_cndmask_b32_e32 v0, v179, v187, vcc
	v_or_b32_e32 v16, 0x100, v12
	v_or_b32_e32 v18, 0x200, v12
	v_or_b32_e32 v20, 0x300, v12
	v_readlane_b32 s1, v254, 47
	v_lshlrev_b32_e32 v57, 2, v0
	v_lshl_add_u64 v[0:1], s[2:3], 0, v[14:15]
	global_load_dwordx4 v[100:103], v[0:1], off
	global_load_dwordx4 v[104:107], v[0:1], off offset:1024
	global_load_dwordx4 v[108:111], v[0:1], off offset:2048
	global_load_dwordx4 v[112:115], v[0:1], off offset:3072
	s_movk_i32 s1, 0x3000
	s_mov_b64 s[38:39], 0
	v_lshlrev_b32_e32 v40, 2, v12
	v_lshlrev_b32_e32 v42, 2, v16
	v_lshlrev_b32_e32 v44, 2, v18
	v_lshlrev_b32_e32 v46, 2, v20
	v_readlane_b32 s45, v254, 49
	v_readlane_b32 s48, v254, 52
	v_readlane_b32 s49, v254, 53
	v_readlane_b32 s50, v254, 54
	v_readlane_b32 s51, v254, 55
	v_lshlrev_b32_e32 v156, 4, v168
	v_add_u32_e32 v158, 0x1000, v156
	v_readlane_b32 s0, v252, 36
	v_readlane_b32 s1, v252, 37
	v_readlane_b32 s2, v254, 61
	s_mul_i32 s2, s2, 0x1e000
	s_add_u32 s0, s0, s2
	s_addc_u32 s1, s1, 0
	global_load_dwordx4 v[116:119], v156, s[0:1]
	global_load_dwordx4 v[120:123], v158, s[0:1]
	s_add_u32 s0, s0, 0x6000
	s_addc_u32 s1, s1, 0
	global_load_dwordx4 v[124:127], v156, s[0:1]
	global_load_dwordx4 v[128:131], v158, s[0:1]
	s_add_u32 s0, s0, 0x6000
	s_addc_u32 s1, s1, 0
	global_load_dwordx4 v[132:135], v156, s[0:1]
	global_load_dwordx4 v[136:139], v158, s[0:1]
	s_add_u32 s0, s0, 0x6000
	s_addc_u32 s1, s1, 0
	global_load_dwordx4 v[140:143], v156, s[0:1]
	global_load_dwordx4 v[144:147], v158, s[0:1]
	s_add_u32 s0, s0, 0x6000
	s_addc_u32 s1, s1, 0
	global_load_dwordx4 v[148:151], v156, s[0:1]
	global_load_dwordx4 v[152:155], v158, s[0:1]
	s_waitcnt vmcnt(0)
	ds_write_b128 v156, v[116:119]
	ds_write_b128 v156, v[120:123] offset:4096
	ds_write_b128 v156, v[124:127] offset:8192
	ds_write_b128 v156, v[128:131] offset:12288
	ds_write_b128 v156, v[132:135] offset:16384
	ds_write_b128 v156, v[136:139] offset:20480
	ds_write_b128 v156, v[140:143] offset:24576
	ds_write_b128 v156, v[144:147] offset:28672
	ds_write_b128 v156, v[148:151] offset:32768
	ds_write_b128 v156, v[152:155] offset:36864
	s_waitcnt lgkmcnt(0)
	s_barrier
	v_readlane_b32 s0, v254, 46
	s_movk_i32 s1, 0x3000
	s_branch .LBB0_134
.LBB0_133:
	s_or_b64 exec, exec, s[42:43]
	s_and_b64 s[2:3], exec, vcc
	s_or_b64 s[38:39], s[2:3], s[38:39]
	v_add_u32_e32 v43, 0x1000, v41
	v_lshrrev_b32_e32 v41, 11, v41
	s_movk_i32 s2, 0xfff
	v_add_u32_e32 v41, 1, v41
	v_cmp_lt_i32_e32 vcc, s2, v43
	v_readlane_b32 s2, v254, 61
	v_readlane_b32 s3, v254, 62
	v_cndmask_b32_e32 v41, 0, v41, vcc
	v_lshl_add_u32 v157, v41, 13, v40
	ds_read_b128 v[116:119], v157
	ds_read_b128 v[120:123], v157 offset:1024
	ds_read_b128 v[124:127], v157 offset:2048
	ds_read_b128 v[128:131], v157 offset:3072
	ds_read_b128 v[132:135], v157 offset:4096
	ds_read_b128 v[136:139], v157 offset:5120
	ds_read_b128 v[140:143], v157 offset:6144
	ds_read_b128 v[144:147], v157 offset:7168
	s_mul_i32 s2, s2, 5
	v_add_u32_e32 v41, s2, v41
	v_readlane_b32 s2, v252, 36
	v_readlane_b32 s3, v252, 37
	v_mul_f32_e32 v45, v33, v33
	v_mov_b64_e32 v[50:51], s[2:3]
	v_mad_i64_i32 v[52:53], s[2:3], v41, s97, v[50:51]
	s_mov_b64 s[2:3], 0x1000
	s_nop 0
	v_lshl_add_u64 v[50:51], v[52:53], 0, s[2:3]
	v_mov_b32_e32 v41, v2
	v_lshl_add_u64 v[52:53], v[52:53], 0, v[40:41]
	v_lshl_add_u64 v[68:69], v[50:51], 0, v[40:41]
	v_mul_f32_e32 v47, v29, v29
	v_fmac_f32_e32 v45, v32, v32
	v_fmac_f32_e32 v47, v28, v28
	v_fmac_f32_e32 v45, v34, v34
	v_fmac_f32_e32 v47, v30, v30
	v_fmac_f32_e32 v45, v35, v35
	v_fmac_f32_e32 v47, v31, v31
	v_add_f32_e32 v45, v45, v47
	v_mul_f32_e32 v47, v25, v25
	v_fmac_f32_e32 v47, v24, v24
	v_fmac_f32_e32 v47, v26, v26
	v_fmac_f32_e32 v47, v27, v27
	v_add_f32_e32 v45, v47, v45
	v_mul_f32_e32 v47, v5, v5
	v_fmac_f32_e32 v47, v4, v4
	v_fmac_f32_e32 v47, v6, v6
	v_fmac_f32_e32 v47, v7, v7
	v_add_f32_e32 v45, v47, v45
	ds_bpermute_b32 v47, v3, v45
	v_mov_b32_e32 v43, v2
	v_readlane_b32 s2, v254, 11
	v_readlane_b32 s3, v254, 12
	v_mov_b32_e32 v41, v58
	s_waitcnt lgkmcnt(0)
	v_add_f32_e32 v45, v45, v47
	ds_bpermute_b32 v47, v49, v45
	s_waitcnt lgkmcnt(0)
	v_add_f32_e32 v45, v45, v47
	ds_bpermute_b32 v47, v54, v45
	s_waitcnt lgkmcnt(0)
	v_add_f32_e32 v45, v45, v47
	ds_bpermute_b32 v47, v55, v45
	s_waitcnt lgkmcnt(0)
	v_add_f32_e32 v45, v45, v47
	ds_bpermute_b32 v47, v56, v45
	s_waitcnt lgkmcnt(0)
	v_add_f32_e32 v45, v45, v47
	ds_bpermute_b32 v47, v57, v45
	s_waitcnt lgkmcnt(0)
	v_add_f32_e32 v45, v45, v47
	v_fmamk_f32 v45, v45, 0x3a800000, v174
	v_rsq_f32_e32 v48, v45
	v_mov_b32_e32 v45, v2
	v_mov_b32_e32 v47, v2
	v_pk_mul_f32 v[34:35], v[34:35], v[48:49] op_sel_hi:[1,0]
	v_pk_mul_f32 v[32:33], v[32:33], v[48:49] op_sel_hi:[1,0]
	v_pk_mul_f32 v[30:31], v[30:31], v[48:49] op_sel_hi:[1,0]
	v_pk_mul_f32 v[28:29], v[28:29], v[48:49] op_sel_hi:[1,0]
	v_pk_mul_f32 v[26:27], v[26:27], v[48:49] op_sel_hi:[1,0]
	v_pk_mul_f32 v[24:25], v[24:25], v[48:49] op_sel_hi:[1,0]
	v_pk_mul_f32 v[6:7], v[6:7], v[48:49] op_sel_hi:[1,0]
	v_pk_mul_f32 v[4:5], v[4:5], v[48:49] op_sel_hi:[1,0]
	v_pk_mul_f32 v[32:33], v[100:101], v[32:33]
	v_pk_mul_f32 v[34:35], v[102:103], v[34:35]
	v_pk_add_f32 v[60:61], v[134:135], 1.0 op_sel_hi:[1,0]
	v_pk_add_f32 v[62:63], v[132:133], 1.0 op_sel_hi:[1,0]
	v_pk_fma_f32 v[34:35], v[60:61], v[34:35], v[118:119]
	v_pk_fma_f32 v[32:33], v[62:63], v[32:33], v[116:117]
	v_cvt_pk_bf16_f32 v32, v32, v33
	v_cvt_pk_bf16_f32 v33, v34, v35
	global_store_dwordx2 v[36:37], v[32:33], off
	v_pk_mul_f32 v[28:29], v[104:105], v[28:29]
	v_pk_mul_f32 v[30:31], v[106:107], v[30:31]
	v_pk_add_f32 v[60:61], v[138:139], 1.0 op_sel_hi:[1,0]
	v_pk_add_f32 v[62:63], v[136:137], 1.0 op_sel_hi:[1,0]
	v_pk_fma_f32 v[30:31], v[60:61], v[30:31], v[122:123]
	v_pk_fma_f32 v[28:29], v[62:63], v[28:29], v[120:121]
	v_cvt_pk_bf16_f32 v28, v28, v29
	v_cvt_pk_bf16_f32 v29, v30, v31
	global_store_dwordx2 v[36:37], v[28:29], off offset:512
	v_pk_mul_f32 v[24:25], v[108:109], v[24:25]
	v_pk_mul_f32 v[26:27], v[110:111], v[26:27]
	v_pk_add_f32 v[60:61], v[142:143], 1.0 op_sel_hi:[1,0]
	v_pk_add_f32 v[62:63], v[140:141], 1.0 op_sel_hi:[1,0]
	v_pk_fma_f32 v[26:27], v[60:61], v[26:27], v[126:127]
	v_pk_fma_f32 v[24:25], v[62:63], v[24:25], v[124:125]
	v_cvt_pk_bf16_f32 v24, v24, v25
	v_cvt_pk_bf16_f32 v25, v26, v27
	global_store_dwordx2 v[36:37], v[24:25], off offset:1024
	v_pk_mul_f32 v[4:5], v[112:113], v[4:5]
	v_pk_mul_f32 v[6:7], v[114:115], v[6:7]
	v_pk_add_f32 v[60:61], v[146:147], 1.0 op_sel_hi:[1,0]
	v_pk_add_f32 v[62:63], v[144:145], 1.0 op_sel_hi:[1,0]
	v_pk_fma_f32 v[6:7], v[60:61], v[6:7], v[130:131]
	v_pk_fma_f32 v[4:5], v[62:63], v[4:5], v[128:129]
	v_cvt_pk_bf16_f32 v4, v4, v5
	v_cvt_pk_bf16_f32 v5, v6, v7
	global_store_dwordx2 v[36:37], v[4:5], off offset:1536
	s_waitcnt vmcnt(4)
	v_mov_b32_e32 v32, v12
	v_lshl_add_u64 v[36:37], v[36:37], 0, s[2:3]
	v_readlane_b32 s2, v254, 9
	v_readlane_b32 s3, v254, 10
	v_mov_b32_e32 v33, v13
	v_mov_b32_e32 v34, v14
	v_lshl_add_u64 v[38:39], v[38:39], 0, s[2:3]
	v_mov_b32_e32 v35, v15
	v_mov_b32_e32 v28, v16
	v_mov_b32_e32 v29, v17
	v_mov_b32_e32 v30, v18
	v_mov_b32_e32 v31, v19
	v_mov_b32_e32 v24, v20
	v_mov_b32_e32 v25, v21
	v_mov_b32_e32 v26, v22
	v_mov_b32_e32 v27, v23
	v_mov_b32_e32 v4, v8
	v_mov_b32_e32 v5, v9
	v_mov_b32_e32 v6, v10
	v_mov_b32_e32 v7, v11
	s_andn2_b64 exec, exec, s[38:39]
	s_cbranch_execz .LBB0_136

.LBB0_177:
	s_or_b64 exec, exec, s[36:37]
	v_mov_b32_e32 v11, v168
	v_mov_b32_e32 v0, v168
	v_readlane_b32 s0, v254, 7
	v_ashrrev_i32_e32 v10, 6, v0
	s_nop 0
	v_add_u32_e32 v8, s0, v10
	v_cmp_gt_i32_e32 vcc, s1, v8
	s_and_saveexec_b64 s[38:39], vcc
	v_readlane_b32 s0, v254, 46
	v_readlane_b32 s1, v254, 47
	s_cbranch_execz .LBB0_182
	v_ashrrev_i32_e32 v9, 31, v8
	v_readlane_b32 s40, v254, 48
	v_lshlrev_b32_e32 v3, 2, v11
	v_lshlrev_b64 v[0:1], 12, v[8:9]
	v_readlane_b32 s42, v254, 50
	v_readlane_b32 s43, v254, 51
	v_and_b32_e32 v12, 0xfc, v3
	v_lshlrev_b32_e32 v14, 2, v12
	v_lshl_add_u64 v[0:1], s[42:43], 0, v[0:1]
	v_mov_b32_e32 v15, v2
	v_lshl_add_u64 v[0:1], v[0:1], 0, v[14:15]
	global_load_dwordx4 v[32:35], v[0:1], off
	global_load_dwordx4 v[28:31], v[0:1], off offset:1024
	global_load_dwordx4 v[24:27], v[0:1], off offset:2048
	global_load_dwordx4 v[4:7], v[0:1], off offset:3072
	v_cmp_lt_i32_e32 vcc, v180, v182
	v_readlane_b32 s0, v255, 0
	v_readlane_b32 s1, v255, 1
	v_cndmask_b32_e32 v0, v179, v180, vcc
	v_cmp_lt_i32_e32 vcc, v183, v182
	v_lshlrev_b32_e32 v3, 2, v0
	v_lshlrev_b64 v[8:9], 11, v[8:9]
	v_cndmask_b32_e32 v0, v179, v183, vcc
	v_cmp_lt_i32_e32 vcc, v184, v182
	v_lshlrev_b32_e32 v49, 2, v0
	v_and_b32_e32 v11, 63, v11
	v_cndmask_b32_e32 v0, v179, v184, vcc
	v_cmp_lt_i32_e32 vcc, v185, v182
	v_lshlrev_b32_e32 v54, 2, v0
	v_lshl_or_b32 v8, v11, 3, v8
	v_cndmask_b32_e32 v0, v179, v185, vcc
	v_cmp_lt_i32_e32 vcc, v186, v182
	v_lshlrev_b32_e32 v55, 2, v0
	v_readlane_b32 s41, v254, 49
	v_cndmask_b32_e32 v0, v179, v186, vcc
	v_cmp_lt_i32_e32 vcc, v187, v182
	v_lshlrev_b32_e32 v56, 2, v0
	v_or_b32_e32 v16, 0x100, v12
	v_cndmask_b32_e32 v0, v179, v187, vcc
	v_lshlrev_b32_e32 v57, 2, v0
	v_lshl_add_u64 v[0:1], s[0:1], 0, v[14:15]
	global_load_dwordx4 v[100:103], v[0:1], off
	global_load_dwordx4 v[104:107], v[0:1], off offset:1024
	global_load_dwordx4 v[108:111], v[0:1], off offset:2048
	global_load_dwordx4 v[112:115], v[0:1], off offset:3072
	v_readlane_b32 s0, v252, 32
	v_readlane_b32 s1, v252, 33
	v_or_b32_e32 v18, 0x200, v12
	v_or_b32_e32 v20, 0x300, v12
	v_lshl_add_u64 v[36:37], s[0:1], 0, v[8:9]
	v_readlane_b32 s0, v254, 8
	s_mov_b64 s[40:41], 0
	v_lshlrev_b32_e32 v40, 2, v12
	v_add_u32_e32 v41, s0, v10
	v_readlane_b32 s0, v254, 2
	v_lshlrev_b32_e32 v42, 2, v16
	v_lshlrev_b32_e32 v44, 2, v18
	v_add_u32_e32 v8, s0, v10
	v_ashrrev_i32_e32 v9, 31, v8
	v_lshlrev_b64 v[8:9], 12, v[8:9]
	v_readlane_b32 s0, v250, 51
	v_lshl_or_b32 v8, v11, 4, v8
	v_readlane_b32 s1, v250, 52
	v_lshlrev_b32_e32 v46, 2, v20
	v_readlane_b32 s44, v254, 52
	v_lshl_add_u64 v[38:39], s[0:1], 0, v[8:9]
	v_readlane_b32 s0, v254, 46
	v_readlane_b32 s1, v254, 47
	s_movk_i32 s1, 0x3000
	v_readlane_b32 s45, v254, 53
	v_readlane_b32 s46, v254, 54
	v_readlane_b32 s47, v254, 55
	v_lshlrev_b32_e32 v156, 4, v168
	v_add_u32_e32 v158, 0x1000, v156
	v_readlane_b32 s0, v251, 63
	v_readlane_b32 s1, v252, 0
	v_readlane_b32 s2, v254, 61
	s_mul_i32 s2, s2, 0x1e000
	s_add_u32 s0, s0, s2
	s_addc_u32 s1, s1, 0
	global_load_dwordx4 v[116:119], v156, s[0:1]
	global_load_dwordx4 v[120:123], v158, s[0:1]
	s_add_u32 s0, s0, 0x6000
	s_addc_u32 s1, s1, 0
	global_load_dwordx4 v[124:127], v156, s[0:1]
	global_load_dwordx4 v[128:131], v158, s[0:1]
	s_add_u32 s0, s0, 0x6000
	s_addc_u32 s1, s1, 0
	global_load_dwordx4 v[132:135], v156, s[0:1]
	global_load_dwordx4 v[136:139], v158, s[0:1]
	s_add_u32 s0, s0, 0x6000
	s_addc_u32 s1, s1, 0
	global_load_dwordx4 v[140:143], v156, s[0:1]
	global_load_dwordx4 v[144:147], v158, s[0:1]
	s_add_u32 s0, s0, 0x6000
	s_addc_u32 s1, s1, 0
	global_load_dwordx4 v[148:151], v156, s[0:1]
	global_load_dwordx4 v[152:155], v158, s[0:1]
	s_waitcnt vmcnt(0)
	ds_write_b128 v156, v[116:119]
	ds_write_b128 v156, v[120:123] offset:4096
	ds_write_b128 v156, v[124:127] offset:8192
	ds_write_b128 v156, v[128:131] offset:12288
	ds_write_b128 v156, v[132:135] offset:16384
	ds_write_b128 v156, v[136:139] offset:20480
	ds_write_b128 v156, v[140:143] offset:24576
	ds_write_b128 v156, v[144:147] offset:28672
	ds_write_b128 v156, v[148:151] offset:32768
	ds_write_b128 v156, v[152:155] offset:36864
	s_waitcnt lgkmcnt(0)
	s_barrier
	v_readlane_b32 s0, v254, 46
	s_movk_i32 s1, 0x3000
	s_branch .LBB0_180
.LBB0_179:
	s_or_b64 exec, exec, s[42:43]
	s_and_b64 s[2:3], exec, vcc
	s_or_b64 s[40:41], s[2:3], s[40:41]
	v_add_u32_e32 v43, 0x1000, v41
	v_lshrrev_b32_e32 v41, 11, v41
	s_movk_i32 s2, 0xfff
	v_add_u32_e32 v41, 1, v41
	v_cmp_lt_i32_e32 vcc, s2, v43
	v_readlane_b32 s2, v254, 61
	v_readlane_b32 s3, v254, 62
	v_cndmask_b32_e32 v41, 0, v41, vcc
	v_lshl_add_u32 v157, v41, 13, v40
	ds_read_b128 v[116:119], v157
	ds_read_b128 v[120:123], v157 offset:1024
	ds_read_b128 v[124:127], v157 offset:2048
	ds_read_b128 v[128:131], v157 offset:3072
	ds_read_b128 v[132:135], v157 offset:4096
	ds_read_b128 v[136:139], v157 offset:5120
	ds_read_b128 v[140:143], v157 offset:6144
	ds_read_b128 v[144:147], v157 offset:7168
	s_mul_i32 s2, s2, 5
	v_add_u32_e32 v41, s2, v41
	v_readlane_b32 s2, v251, 63
	v_readlane_b32 s3, v252, 0
	v_mul_f32_e32 v45, v33, v33
	v_mov_b64_e32 v[50:51], s[2:3]
	v_mad_i64_i32 v[52:53], s[2:3], v41, s97, v[50:51]
	s_mov_b64 s[2:3], 0x1000
	s_nop 0
	v_lshl_add_u64 v[50:51], v[52:53], 0, s[2:3]
	v_mov_b32_e32 v41, v2
	v_lshl_add_u64 v[52:53], v[52:53], 0, v[40:41]
	v_lshl_add_u64 v[68:69], v[50:51], 0, v[40:41]
	v_mul_f32_e32 v47, v29, v29
	v_fmac_f32_e32 v45, v32, v32
	v_fmac_f32_e32 v47, v28, v28
	v_fmac_f32_e32 v45, v34, v34
	v_fmac_f32_e32 v47, v30, v30
	v_fmac_f32_e32 v45, v35, v35
	v_fmac_f32_e32 v47, v31, v31
	v_add_f32_e32 v45, v45, v47
	v_mul_f32_e32 v47, v25, v25
	v_fmac_f32_e32 v47, v24, v24
	v_fmac_f32_e32 v47, v26, v26
	v_fmac_f32_e32 v47, v27, v27
	v_add_f32_e32 v45, v47, v45
	v_mul_f32_e32 v47, v5, v5
	v_fmac_f32_e32 v47, v4, v4
	v_fmac_f32_e32 v47, v6, v6
	v_fmac_f32_e32 v47, v7, v7
	v_add_f32_e32 v45, v47, v45
	ds_bpermute_b32 v47, v3, v45
	v_mov_b32_e32 v43, v2
	v_readlane_b32 s2, v254, 11
	v_readlane_b32 s3, v254, 12
	v_mov_b32_e32 v41, v58
	s_waitcnt lgkmcnt(0)
	v_add_f32_e32 v45, v45, v47
	ds_bpermute_b32 v47, v49, v45
	s_waitcnt lgkmcnt(0)
	v_add_f32_e32 v45, v45, v47
	ds_bpermute_b32 v47, v54, v45
	s_waitcnt lgkmcnt(0)
	v_add_f32_e32 v45, v45, v47
	ds_bpermute_b32 v47, v55, v45
	s_waitcnt lgkmcnt(0)
	v_add_f32_e32 v45, v45, v47
	ds_bpermute_b32 v47, v56, v45
	s_waitcnt lgkmcnt(0)
	v_add_f32_e32 v45, v45, v47
	ds_bpermute_b32 v47, v57, v45
	s_waitcnt lgkmcnt(0)
	v_add_f32_e32 v45, v45, v47
	v_fmamk_f32 v45, v45, 0x3a800000, v174
	v_rsq_f32_e32 v48, v45
	v_mov_b32_e32 v45, v2
	v_mov_b32_e32 v47, v2
	v_pk_mul_f32 v[34:35], v[34:35], v[48:49] op_sel_hi:[1,0]
	v_pk_mul_f32 v[32:33], v[32:33], v[48:49] op_sel_hi:[1,0]
	v_pk_mul_f32 v[30:31], v[30:31], v[48:49] op_sel_hi:[1,0]
	v_pk_mul_f32 v[28:29], v[28:29], v[48:49] op_sel_hi:[1,0]
	v_pk_mul_f32 v[26:27], v[26:27], v[48:49] op_sel_hi:[1,0]
	v_pk_mul_f32 v[24:25], v[24:25], v[48:49] op_sel_hi:[1,0]
	v_pk_mul_f32 v[6:7], v[6:7], v[48:49] op_sel_hi:[1,0]
	v_pk_mul_f32 v[4:5], v[4:5], v[48:49] op_sel_hi:[1,0]
	v_pk_mul_f32 v[32:33], v[100:101], v[32:33]
	v_pk_mul_f32 v[34:35], v[102:103], v[34:35]
	v_pk_add_f32 v[60:61], v[134:135], 1.0 op_sel_hi:[1,0]
	v_pk_add_f32 v[62:63], v[132:133], 1.0 op_sel_hi:[1,0]
	v_pk_fma_f32 v[34:35], v[60:61], v[34:35], v[118:119]
	v_pk_fma_f32 v[32:33], v[62:63], v[32:33], v[116:117]
	v_cvt_pk_bf16_f32 v32, v32, v33
	v_cvt_pk_bf16_f32 v33, v34, v35
	global_store_dwordx2 v[36:37], v[32:33], off
	v_pk_mul_f32 v[28:29], v[104:105], v[28:29]
	v_pk_mul_f32 v[30:31], v[106:107], v[30:31]
	v_pk_add_f32 v[60:61], v[138:139], 1.0 op_sel_hi:[1,0]
	v_pk_add_f32 v[62:63], v[136:137], 1.0 op_sel_hi:[1,0]
	v_pk_fma_f32 v[30:31], v[60:61], v[30:31], v[122:123]
	v_pk_fma_f32 v[28:29], v[62:63], v[28:29], v[120:121]
	v_cvt_pk_bf16_f32 v28, v28, v29
	v_cvt_pk_bf16_f32 v29, v30, v31
	global_store_dwordx2 v[36:37], v[28:29], off offset:512
	v_pk_mul_f32 v[24:25], v[108:109], v[24:25]
	v_pk_mul_f32 v[26:27], v[110:111], v[26:27]
	v_pk_add_f32 v[60:61], v[142:143], 1.0 op_sel_hi:[1,0]
	v_pk_add_f32 v[62:63], v[140:141], 1.0 op_sel_hi:[1,0]
	v_pk_fma_f32 v[26:27], v[60:61], v[26:27], v[126:127]
	v_pk_fma_f32 v[24:25], v[62:63], v[24:25], v[124:125]
	v_cvt_pk_bf16_f32 v24, v24, v25
	v_cvt_pk_bf16_f32 v25, v26, v27
	global_store_dwordx2 v[36:37], v[24:25], off offset:1024
	v_pk_mul_f32 v[4:5], v[112:113], v[4:5]
	v_pk_mul_f32 v[6:7], v[114:115], v[6:7]
	v_pk_add_f32 v[60:61], v[146:147], 1.0 op_sel_hi:[1,0]
	v_pk_add_f32 v[62:63], v[144:145], 1.0 op_sel_hi:[1,0]
	v_pk_fma_f32 v[6:7], v[60:61], v[6:7], v[130:131]
	v_pk_fma_f32 v[4:5], v[62:63], v[4:5], v[128:129]
	v_cvt_pk_bf16_f32 v4, v4, v5
	v_cvt_pk_bf16_f32 v5, v6, v7
	global_store_dwordx2 v[36:37], v[4:5], off offset:1536
	s_waitcnt vmcnt(4)
	v_mov_b32_e32 v32, v12
	v_lshl_add_u64 v[36:37], v[36:37], 0, s[2:3]
	v_readlane_b32 s2, v254, 9
	v_readlane_b32 s3, v254, 10
	v_mov_b32_e32 v33, v13
	v_mov_b32_e32 v34, v14
	v_lshl_add_u64 v[38:39], v[38:39], 0, s[2:3]
	v_mov_b32_e32 v35, v15
	v_mov_b32_e32 v28, v16
	v_mov_b32_e32 v29, v17
	v_mov_b32_e32 v30, v18
	v_mov_b32_e32 v31, v19
	v_mov_b32_e32 v24, v20
	v_mov_b32_e32 v25, v21
	v_mov_b32_e32 v26, v22
	v_mov_b32_e32 v27, v23
	v_mov_b32_e32 v4, v8
	v_mov_b32_e32 v5, v9
	v_mov_b32_e32 v6, v10
	v_mov_b32_e32 v7, v11
	s_andn2_b64 exec, exec, s[40:41]
	s_cbranch_execz .LBB0_182
